# hyena long-conv items: the 8 input-row loads and the 8 filter-row loads per order issued together instead of one load per loop trip; gdn state-update fragment reads ring-scheduled
# speedup vs baseline: 1.0327x; 1.0182x over previous
; #define LAS __attribute__((address_space(3)))
; __device__ __forceinline__ unsigned pk2(float lo, float hi) { const f32v2_t f = {lo, hi}; const bf16v2_t b = __builtin_convertvector(f, bf16v2_t); return __builtin_bit_cast(unsigned, b); }
; #define WAVE_SYNC() do { asm volatile("s_waitcnt lgkmcnt(0)" ::: "memory"); __builtin_amdgcn_wave_barrier(); asm volatile("" ::: "memory"); } while (0)
; #define MFMA16(a, b, c) __builtin_amdgcn_mfma_f32_16x16x32_bf16((a), (b), (c), 0, 0, 0)
; template <int MODE>
; __device__ NOINL void chain_item(const LAS Params* lp, int l, int item, bool ctx_out, LAS unsigned char* lds) {
;     ...
;         for (int dk = 0; dk < NDK; ++dk) { u32x2 pk; pk.x = pk2(Sacc[dk][0], Sacc[dk][1]); pk.y = pk2(Sacc[dk][2], Sacc[dk][3]); *(LAS u32x2*)(ST + fr * 136 + 16 * dk + 4 * fq) = pk; }
;         WAVE_SYNC();
;         f32x4 qs[4], ksm[4];
; #pragma unroll
;         for (int ct = 0; ct < 4; ++ct) { qs[ct] = (f32x4){0.f, 0.f, 0.f, 0.f}; ksm[ct] = (f32x4){0.f, 0.f, 0.f, 0.f}; }
; #pragma unroll
;         for (int ks = 0; ks < NKS; ++ks) {
;             const bf16x8 Bf = *(const LAS bf16x8*)(ST + fr * 136 + ks * 32 + fq * 8);
; #pragma unroll
;             for (int ct = 0; ct < 4; ++ct) {
;                 const bf16x8 Aq = *(const LAS bf16x8*)(Qs + (16 * ct + fr) * 136 + kcol + ks * 32 + fq * 8);
;                 qs[ct] = MFMA16(Aq, Bf, qs[ct]);
;                 if (MODE == 0) { const bf16x8 Ak = *(const LAS bf16x8*)(Ks + (16 * ct + fr) * 136 + ks * 32 + fq * 8); ksm[ct] = MFMA16(Ak, Bf, ksm[ct]); }
;             }
;         }
.LBB0_1141:
	s_or_b64 exec, exec, s[62:63]
	ds_write_b16 v178, v68
	v_cvt_pk_bf16_f32 v68, v28, v29
	v_cvt_pk_bf16_f32 v69, v30, v31
	v_cvt_pk_bf16_f32 v70, v40, v41
	v_cvt_pk_bf16_f32 v71, v42, v43
	s_waitcnt lgkmcnt(0)
	s_barrier
	ds_write2_b64 v113, v[68:69], v[70:71] offset1:4
	v_cvt_pk_bf16_f32 v68, v32, v33
	v_cvt_pk_bf16_f32 v69, v34, v35
	v_cvt_pk_bf16_f32 v70, v36, v37
	v_cvt_pk_bf16_f32 v71, v38, v39
	ds_write2_b64 v113, v[68:69], v[70:71] offset0:8 offset1:12
	v_cvt_pk_bf16_f32 v68, v56, v57
	v_cvt_pk_bf16_f32 v69, v58, v59
	v_cvt_pk_bf16_f32 v70, v52, v53
	v_cvt_pk_bf16_f32 v71, v54, v55
	ds_write2_b64 v113, v[68:69], v[70:71] offset0:16 offset1:20
	v_cvt_pk_bf16_f32 v68, v44, v45
	v_cvt_pk_bf16_f32 v69, v46, v47
	v_cvt_pk_bf16_f32 v70, v48, v49
	v_cvt_pk_bf16_f32 v71, v50, v51
	ds_write2_b64 v113, v[68:69], v[70:71] offset0:24 offset1:28
	s_waitcnt lgkmcnt(0)
	v_add_u32_e32 v119, v113, v154
	ds_read_b128 v[68:71], v119
	ds_read_b128 v[72:75], v179
	ds_read_b128 v[76:79], v179 offset:17408
	ds_read_b128 v[96:99], v179 offset:13056
	ds_read_b128 v[80:83], v179 offset:4352
	ds_read_b128 v[88:91], v179 offset:8704
	ds_read_b128 v[84:87], v179 offset:21760
	ds_read_b128 v[92:95], v179 offset:26112
	ds_read_b128 v[100:103], v179 offset:30464
	s_waitcnt lgkmcnt(7)
	v_mfma_f32_16x16x32_bf16 v[72:75], v[72:75], v[68:71], 0
	v_add_u32_e32 v121, 0x25500, v110
	s_add_i32 s5, s4, 4
	s_and_b64 s[20:21], vcc, exec
	s_waitcnt lgkmcnt(6)
	v_mfma_f32_16x16x32_bf16 v[76:79], v[76:79], v[68:71], 0
	s_cselect_b32 s5, s1, s5
	s_add_i32 s22, s4, 40
	s_and_b64 s[20:21], vcc, exec
	s_waitcnt lgkmcnt(4)
	v_mfma_f32_16x16x32_bf16 v[80:83], v[80:83], v[68:71], 0
	s_cselect_b32 s20, s1, s22
	s_cmp_lt_u32 s1, 4
	s_cselect_b32 s1, s5, s20
	s_waitcnt lgkmcnt(2)
	v_mfma_f32_16x16x32_bf16 v[84:87], v[84:87], v[68:71], 0
	s_lshl_b32 s5, s1, 6
	s_add_i32 s20, s18, s5
	s_or_b32 s5, s5, s38
	v_mfma_f32_16x16x32_bf16 v[88:91], v[88:91], v[68:71], 0
	s_cmp_lt_u32 s1, 4
	s_cselect_b32 s1, s5, s20
	s_mul_hi_i32 s21, s1, s19
	s_waitcnt lgkmcnt(1)
	v_mfma_f32_16x16x32_bf16 v[92:95], v[92:95], v[68:71], 0
	s_mul_i32 s20, s1, s19
	v_mov_b32_e32 v123, v1
	v_mov_b32_e32 v125, v1
	v_mfma_f32_16x16x32_bf16 v[96:99], v[96:99], v[68:71], 0
	v_mov_b32_e32 v127, v1
	v_mov_b32_e32 v129, v1
	v_mov_b32_e32 v131, v1
	s_waitcnt lgkmcnt(0)
	v_mfma_f32_16x16x32_bf16 v[68:71], v[100:103], v[68:71], 0
	ds_read_b128 v[100:103], v119 offset:64
	ds_read_b128 v[104:107], v179 offset:64
	v_mov_b32_e32 v133, v1
	v_mov_b32_e32 v135, v1
	s_waitcnt lgkmcnt(0)
	v_mfma_f32_16x16x32_bf16 v[72:75], v[104:107], v[100:103], v[72:75]
	ds_read_b128 v[104:107], v179 offset:17472
	v_mov_b32_e32 v137, v1
	v_mov_b32_e32 v139, v1
	s_waitcnt lgkmcnt(0)
	v_mfma_f32_16x16x32_bf16 v[76:79], v[104:107], v[100:103], v[76:79]
	ds_read_b128 v[104:107], v179 offset:4416
	v_mov_b32_e32 v141, v1
	v_mov_b32_e32 v143, v1
	s_waitcnt lgkmcnt(0)
	v_mfma_f32_16x16x32_bf16 v[80:83], v[104:107], v[100:103], v[80:83]
	ds_read_b128 v[104:107], v179 offset:21824
	v_mov_b32_e32 v145, v1
	v_mov_b32_e32 v147, v1
	s_waitcnt lgkmcnt(0)
	v_mfma_f32_16x16x32_bf16 v[84:87], v[104:107], v[100:103], v[84:87]
	ds_read_b128 v[104:107], v179 offset:8768
	s_add_i32 s4, s4, -1
	s_cmp_lg_u32 s0, 36
	s_waitcnt lgkmcnt(0)
	v_mfma_f32_16x16x32_bf16 v[88:91], v[104:107], v[100:103], v[88:91]
	ds_read_b128 v[104:107], v179 offset:26176
	s_mov_b32 s1, s0
	s_waitcnt lgkmcnt(0)
	v_mfma_f32_16x16x32_bf16 v[92:95], v[104:107], v[100:103], v[92:95]
	ds_read_b128 v[104:107], v179 offset:13120
	s_waitcnt lgkmcnt(0)
	v_mfma_f32_16x16x32_bf16 v[96:99], v[104:107], v[100:103], v[96:99]
	ds_read_b128 v[104:107], v179 offset:30528
	s_waitcnt lgkmcnt(0)
	v_mfma_f32_16x16x32_bf16 v[68:71], v[104:107], v[100:103], v[68:71]
	ds_read_b128 v[100:103], v119 offset:128
	ds_read_b128 v[104:107], v179 offset:128
	s_waitcnt lgkmcnt(0)
	v_mfma_f32_16x16x32_bf16 v[72:75], v[104:107], v[100:103], v[72:75]
	ds_read_b128 v[104:107], v179 offset:17536
	s_waitcnt lgkmcnt(0)
	v_mfma_f32_16x16x32_bf16 v[76:79], v[104:107], v[100:103], v[76:79]
	ds_read_b128 v[104:107], v179 offset:4480
	s_waitcnt lgkmcnt(0)
	v_mfma_f32_16x16x32_bf16 v[80:83], v[104:107], v[100:103], v[80:83]
	ds_read_b128 v[104:107], v179 offset:21888
	s_waitcnt lgkmcnt(0)
	v_mfma_f32_16x16x32_bf16 v[84:87], v[104:107], v[100:103], v[84:87]
	ds_read_b128 v[104:107], v179 offset:8832
	s_waitcnt lgkmcnt(0)
	v_mfma_f32_16x16x32_bf16 v[88:91], v[104:107], v[100:103], v[88:91]
	ds_read_b128 v[104:107], v179 offset:26240
	s_waitcnt lgkmcnt(0)
	v_mfma_f32_16x16x32_bf16 v[104:107], v[104:107], v[100:103], v[92:95]
	s_nop 2
	ds_read_b128 v[92:95], v179 offset:13184
	s_waitcnt lgkmcnt(0)
	v_mfma_f32_16x16x32_bf16 v[194:197], v[92:95], v[100:103], v[96:99]
	ds_read_b128 v[92:95], v179 offset:30592
	s_waitcnt lgkmcnt(0)
	v_mfma_f32_16x16x32_bf16 v[68:71], v[92:95], v[100:103], v[68:71]
	ds_read_b128 v[100:103], v119 offset:192
	ds_read_b128 v[92:95], v179 offset:192
	v_add_u32_e32 v119, s34, v155
	s_waitcnt lgkmcnt(0)
	v_mfma_f32_16x16x32_bf16 v[96:99], v[92:95], v[100:103], v[72:75]
	s_nop 2
	ds_read_b128 v[72:75], v179 offset:17600
	s_waitcnt lgkmcnt(0)
	v_mfma_f32_16x16x32_bf16 v[198:201], v[72:75], v[100:103], v[76:79]
	ds_read_b128 v[72:75], v179 offset:4544
	s_nop 1
	ds_read_b128 v[76:79], v179 offset:13248
	s_waitcnt lgkmcnt(1)
	v_mfma_f32_16x16x32_bf16 v[92:95], v[72:75], v[100:103], v[80:83]
	ds_read_b128 v[72:75], v179 offset:21952
	s_waitcnt lgkmcnt(0)
	v_mfma_f32_16x16x32_bf16 v[232:235], v[72:75], v[100:103], v[84:87]
	ds_read_b128 v[72:75], v179 offset:8896
	s_nop 1
	ds_read_b128 v[84:87], v179 offset:30656
	s_waitcnt lgkmcnt(1)
; #define LAS __attribute__((address_space(3)))
; template <int MODE>
; __device__ NOINL void chain_item(const LAS Params* lp, int l, int item, bool ctx_out, LAS unsigned char* lds) {
;     ...
;         float eg[4][4];
; #pragma unroll
;         for (int ct = 0; ct < 4; ++ct)
; #pragma unroll
;             for (int j = 0; j < 4; ++j) { const int c = 16 * ct + 4 * fq + j; eg[ct][j] = MODE == 0 ? gcs[128 + c] : __expf((float)(c + 1) * lg); }
;         bf16x8 Bv[2];
;         if (MODE == 0) {
; #pragma unroll
;             for (int ct = 0; ct < 4; ++ct) {
;                 const u32x2 vv = *(const LAS u32x2*)(VT + (dvrow + fr) * 72 + (((2 * ct + (fq >> 1)) ^ vkey) << 3) + 4 * (fq & 1));
;                 const float v4[4] = {bflo(vv.x), bfhi(vv.x), bflo(vv.y), bfhi(vv.y)};
;                 float r[4];
; #pragma unroll
;                 for (int j = 0; j < 4; ++j) r[j] = bts[16 * ct + 4 * fq + j] * (v4[j] - eg[ct][j] * ksm[ct][j]);
;                 u32x2 pk; pk.x = pk2(r[0], r[1]); pk.y = pk2(r[2], r[3]);
;                 *(LAS u32x2*)(RP + fr * 72 + 16 * ct + 4 * fq) = pk;
;             }
;             WAVE_SYNC();
;             bf16x8 Br[2];
;             Br[0] = *(const LAS bf16x8*)(RP + fr * 72 + fq * 8); Br[1] = *(const LAS bf16x8*)(RP + fr * 72 + 32 + fq * 8);
;             f32x4 vn[4];
; #pragma unroll
;             for (int ct = 0; ct < 4; ++ct) {
;                 vn[ct] = (f32x4){0.f, 0.f, 0.f, 0.f};
; #pragma unroll
;                 for (int ks = 0; ks < 2; ++ks) { const bf16x8 A = *(const LAS bf16x8*)(TT + (16 * ct + fr) * 72 + ks * 32 + fq * 8); vn[ct] = MFMA16(A, Br[ks], vn[ct]); }
;             }
;             WAVE_SYNC();
; #pragma unroll
;             for (int ct = 0; ct < 4; ++ct) { u32x2 pk; pk.x = pk2(vn[ct][0], vn[ct][1]); pk.y = pk2(vn[ct][2], vn[ct][3]); *(LAS u32x2*)(RP + fr * 72 + 16 * ct + 4 * fq) = pk; }
;             WAVE_SYNC();
;             Bv[0] = *(const LAS bf16x8*)(RP + fr * 72 + fq * 8); Bv[1] = *(const LAS bf16x8*)(RP + fr * 72 + 32 + fq * 8);
;         } else {
;             Bv[0] = *(const LAS bf16x8*)(VT + (dvrow + fr) * 72 + ((fq ^ vkey) << 3)); Bv[1] = *(const LAS bf16x8*)(VT + (dvrow + fr) * 72 + (((4 + fq) ^ vkey) << 3));
;         }
;         {
;             typedef __attribute__((address_space(1))) bf16_t gbf16;
;             bf16_t* ob; int ldo;
	v_mfma_f32_16x16x32_bf16 v[80:83], v[72:75], v[100:103], v[88:91]
	ds_read_b128 v[72:75], v179 offset:26304
	s_nop 1
	ds_read_b64 v[88:89], v186 offset:53248
	s_waitcnt lgkmcnt(0)
	v_lshlrev_b32_e32 v90, 16, v88
	v_mfma_f32_16x16x32_bf16 v[72:75], v[72:75], v[100:103], v[104:107]
	v_and_b32_e32 v91, 0xffff0000, v88
	s_nop 1
	ds_read_b128 v[104:107], v119 offset:512
	v_lshlrev_b32_e32 v88, 16, v89
	v_mfma_f32_16x16x32_bf16 v[68:71], v[84:87], v[100:103], v[68:71]
	ds_read_b128 v[84:87], v121
	v_and_b32_e32 v89, 0xffff0000, v89
	s_waitcnt lgkmcnt(1)
	v_pk_fma_f32 v[90:91], v[198:199], v[104:105], v[90:91] neg_lo:[1,0,0] neg_hi:[1,0,0]
	v_pk_fma_f32 v[88:89], v[200:201], v[106:107], v[88:89] neg_lo:[1,0,0] neg_hi:[1,0,0]
	v_mfma_f32_16x16x32_bf16 v[76:79], v[76:79], v[100:103], v[194:197]
	s_waitcnt lgkmcnt(0)
	v_pk_mul_f32 v[84:85], v[84:85], v[90:91]
	v_pk_mul_f32 v[86:87], v[86:87], v[88:89]
	v_cvt_pk_bf16_f32 v148, v84, v85
	v_cvt_pk_bf16_f32 v149, v86, v87
	ds_read_b128 v[100:103], v119 offset:576
	ds_read_b128 v[88:91], v119 offset:640
	ds_read_b128 v[84:87], v119 offset:704
	ds_write_b64 v158, v[148:149] offset:4352
	ds_read_b64 v[148:149], v187 offset:53248
	ds_read_b128 v[194:197], v121 offset:64
	v_add_u32_e32 v119, v158, v154
	s_waitcnt lgkmcnt(1)
	v_lshlrev_b32_e32 v198, 16, v148
	v_and_b32_e32 v199, 0xffff0000, v148
	v_lshlrev_b32_e32 v148, 16, v149
	v_and_b32_e32 v149, 0xffff0000, v149
	v_pk_fma_f32 v[198:199], v[232:233], v[100:101], v[198:199] neg_lo:[1,0,0] neg_hi:[1,0,0]
	v_pk_fma_f32 v[148:149], v[234:235], v[102:103], v[148:149] neg_lo:[1,0,0] neg_hi:[1,0,0]
	s_waitcnt lgkmcnt(0)
	v_pk_mul_f32 v[194:195], v[194:195], v[198:199]
	v_pk_mul_f32 v[148:149], v[196:197], v[148:149]
	v_cvt_pk_bf16_f32 v194, v194, v195
	v_cvt_pk_bf16_f32 v195, v148, v149
	ds_write_b64 v158, v[194:195] offset:4384
	ds_read_b64 v[148:149], v188 offset:53248
	ds_read_b128 v[194:197], v121 offset:128
	s_waitcnt lgkmcnt(1)
	v_lshlrev_b32_e32 v198, 16, v148
	v_and_b32_e32 v199, 0xffff0000, v148
	v_lshlrev_b32_e32 v148, 16, v149
	v_and_b32_e32 v149, 0xffff0000, v149
	v_pk_fma_f32 v[72:73], v[72:73], v[88:89], v[198:199] neg_lo:[1,0,0] neg_hi:[1,0,0]
	v_pk_fma_f32 v[74:75], v[74:75], v[90:91], v[148:149] neg_lo:[1,0,0] neg_hi:[1,0,0]
	s_waitcnt lgkmcnt(0)
	v_pk_mul_f32 v[72:73], v[194:195], v[72:73]
	v_pk_mul_f32 v[74:75], v[196:197], v[74:75]
	v_cvt_pk_bf16_f32 v72, v72, v73
	v_cvt_pk_bf16_f32 v73, v74, v75
	ds_write_b64 v158, v[72:73] offset:4416
	ds_read_b64 v[72:73], v189 offset:53248
	s_waitcnt lgkmcnt(0)
	v_lshlrev_b32_e32 v148, 16, v72
	v_and_b32_e32 v149, 0xffff0000, v72
	v_lshlrev_b32_e32 v194, 16, v73
	v_and_b32_e32 v195, 0xffff0000, v73
	ds_read_b128 v[72:75], v121 offset:192
	v_pk_fma_f32 v[68:69], v[68:69], v[84:85], v[148:149] neg_lo:[1,0,0] neg_hi:[1,0,0]
	v_pk_fma_f32 v[70:71], v[70:71], v[86:87], v[194:195] neg_lo:[1,0,0] neg_hi:[1,0,0]
	v_add_u32_e32 v121, v159, v157
	v_lshl_add_u64 v[148:149], s[20:21], 1, v[116:117]
	s_waitcnt lgkmcnt(0)
	v_pk_mul_f32 v[68:69], v[72:73], v[68:69]
	v_pk_mul_f32 v[70:71], v[74:75], v[70:71]
	v_cvt_pk_bf16_f32 v68, v68, v69
	v_cvt_pk_bf16_f32 v69, v70, v71
	ds_write_b64 v158, v[68:69] offset:4448
	s_waitcnt lgkmcnt(0)
	ds_read_b128 v[68:71], v119 offset:4352
	ds_read_b128 v[72:75], v119 offset:4416
	ds_read_b128 v[194:197], v121
	ds_read_b128 v[198:201], v121 offset:64
	s_waitcnt lgkmcnt(1)
	v_mfma_f32_16x16x32_bf16 v[194:197], v[194:197], v[68:71], 0
	v_add_u32_e32 v121, v159, v180
	ds_read_b128 v[232:235], v121 offset:64
	ds_read_b128 v[236:239], v121 offset:2368
	s_waitcnt lgkmcnt(2)
	v_mfma_f32_16x16x32_bf16 v[194:197], v[198:201], v[72:75], v[194:197]
	ds_read_b128 v[198:201], v121
	s_waitcnt lgkmcnt(0)
	v_mfma_f32_16x16x32_bf16 v[198:201], v[198:201], v[68:71], 0
	v_mfma_f32_16x16x32_bf16 v[198:201], v[232:235], v[72:75], v[198:201]
	ds_read_b128 v[232:235], v121 offset:2304
	s_waitcnt lgkmcnt(0)
	v_mfma_f32_16x16x32_bf16 v[232:235], v[232:235], v[68:71], 0
	v_mfma_f32_16x16x32_bf16 v[232:235], v[236:239], v[72:75], v[232:235]
	ds_read_b128 v[236:239], v121 offset:4608
	s_waitcnt lgkmcnt(0)
	v_mfma_f32_16x16x32_bf16 v[68:71], v[236:239], v[68:71], 0
	ds_read_b128 v[236:239], v121 offset:4672
	v_add_u32_e32 v121, 0x1000, v158
	s_waitcnt lgkmcnt(0)
	s_waitcnt lgkmcnt(0)
	v_mfma_f32_16x16x32_bf16 v[68:71], v[236:239], v[72:75], v[68:71]
	v_cvt_pk_bf16_f32 v72, v194, v195
	v_cvt_pk_bf16_f32 v73, v196, v197
	v_cvt_pk_bf16_f32 v74, v198, v199
	v_cvt_pk_bf16_f32 v75, v200, v201
	ds_write2_b64 v121, v[72:73], v[74:75] offset0:32 offset1:36
	v_cvt_pk_bf16_f32 v72, v232, v233
	v_cvt_pk_bf16_f32 v73, v234, v235
	s_nop 0
	v_cvt_pk_bf16_f32 v68, v68, v69
	v_cvt_pk_bf16_f32 v69, v70, v71
	ds_write2_b64 v121, v[72:73], v[68:69] offset0:40 offset1:44
	s_waitcnt lgkmcnt(0)
	ds_read_b128 v[72:75], v119 offset:4352
	ds_read_b128 v[68:71], v119 offset:4416
	v_add_u32_e32 v119, v160, v157
	ds_read_b128 v[194:197], v119
	ds_read_b128 v[198:201], v119 offset:64
	s_waitcnt lgkmcnt(1)
	v_mfma_f32_16x16x32_bf16 v[194:197], v[194:197], v[72:75], 0
	v_mov_b32_e32 v119, v1
	v_mov_b32_e32 v121, v1
	s_waitcnt lgkmcnt(0)
	v_mfma_f32_16x16x32_bf16 v[194:197], v[198:201], v[68:71], v[194:197]
	v_lshl_add_u64 v[198:199], v[148:149], 0, v[0:1]
	s_nop 6
	v_fma_f32 v96, v96, v104, v194
	v_cvt_pk_bf16_f32 v96, v96, s0
	global_store_short v[198:199], v96, off
	v_fma_f32 v96, v97, v105, v195
	v_cvt_pk_bf16_f32 v104, v96, s0
	v_lshl_add_u64 v[96:97], v[148:149], 0, v[118:119]
	global_store_short v[96:97], v104, off
	v_fma_f32 v96, v98, v106, v196
	v_cvt_pk_bf16_f32 v98, v96, s0
	v_lshl_add_u64 v[96:97], v[148:149], 0, v[120:121]
	v_fmac_f32_e32 v197, v99, v107
	global_store_short v[96:97], v98, off
	v_cvt_pk_bf16_f32 v98, v197, s0
	v_lshl_add_u64 v[96:97], v[148:149], 0, v[122:123]
	v_add_u32_e32 v119, v160, v180
	global_store_short v[96:97], v98, off
	ds_read_b128 v[96:99], v119
	ds_read_b128 v[104:107], v119 offset:64
	s_waitcnt lgkmcnt(1)
; #define LAS __attribute__((address_space(3)))
; __device__ __forceinline__ bf16_t f2bf(float f) { return (bf16_t)(pk2(f, f) & 0xFFFFu); }
; #define MFMA16(a, b, c) __builtin_amdgcn_mfma_f32_16x16x32_bf16((a), (b), (c), 0, 0, 0)
; template <int MODE>
; __device__ NOINL void chain_item(const LAS Params* lp, int l, int item, bool ctx_out, LAS unsigned char* lds) {
;     ...
;                 for (int j = 0; j < 4; ++j) { const int c = 16 * ct + 4 * fq + j, tok = dir ? 63 - c : c; og[tok * ldo] = f2bf(eg[ct][j] * qs[ct][j] + acc[j]); }
;             }
;         }
;         {
;             const float gl = MODE == 0 ? gcs[128 + 63] : __expf(64.f * lg);
; #pragma unroll
;             for (int dk = 0; dk < NDK; ++dk) {
;                 Sacc[dk] = Sacc[dk] * gl;
; #pragma unroll
;                 for (int ks = 0; ks < 2; ++ks) { const bf16x8 A = *(const LAS bf16x8*)(KT + (kcol + 16 * dk + fr) * 72 + (((ks * 4 + fq) ^ (((kcol >> 4) + dk) & 7)) << 3)); Sacc[dk] = MFMA16(A, Bv[ks], Sacc[dk]); }
;             }
	v_mfma_f32_16x16x32_bf16 v[96:99], v[96:99], v[72:75], 0
	s_waitcnt lgkmcnt(0)
	v_mfma_f32_16x16x32_bf16 v[96:99], v[104:107], v[68:71], v[96:99]
	v_lshl_add_u64 v[104:105], v[148:149], 0, v[124:125]
	s_nop 6
	v_fma_f32 v92, v92, v100, v96
	v_cvt_pk_bf16_f32 v92, v92, s0
	global_store_short v[104:105], v92, off
	v_fma_f32 v92, v93, v101, v97
	v_cvt_pk_bf16_f32 v96, v92, s0
	v_lshl_add_u64 v[92:93], v[148:149], 0, v[126:127]
	global_store_short v[92:93], v96, off
	v_fma_f32 v92, v94, v102, v98
	v_cvt_pk_bf16_f32 v94, v92, s0
	v_lshl_add_u64 v[92:93], v[148:149], 0, v[128:129]
	v_fmac_f32_e32 v99, v95, v103
	global_store_short v[92:93], v94, off
	v_cvt_pk_bf16_f32 v94, v99, s0
	v_lshl_add_u64 v[92:93], v[148:149], 0, v[130:131]
	global_store_short v[92:93], v94, off
	ds_read_b128 v[92:95], v119 offset:2304
	ds_read_b128 v[96:99], v119 offset:2368
	s_waitcnt lgkmcnt(1)
	v_mfma_f32_16x16x32_bf16 v[92:95], v[92:95], v[72:75], 0
	s_waitcnt lgkmcnt(0)
	v_mfma_f32_16x16x32_bf16 v[92:95], v[96:99], v[68:71], v[92:95]
	v_lshl_add_u64 v[96:97], v[148:149], 0, v[132:133]
	s_nop 6
	v_fma_f32 v80, v80, v88, v92
	v_cvt_pk_bf16_f32 v80, v80, s0
	global_store_short v[96:97], v80, off
	v_fma_f32 v80, v81, v89, v93
	v_cvt_pk_bf16_f32 v88, v80, s0
	v_lshl_add_u64 v[80:81], v[148:149], 0, v[134:135]
	global_store_short v[80:81], v88, off
	v_fma_f32 v80, v82, v90, v94
	v_cvt_pk_bf16_f32 v82, v80, s0
	v_lshl_add_u64 v[80:81], v[148:149], 0, v[136:137]
	v_fmac_f32_e32 v95, v83, v91
	global_store_short v[80:81], v82, off
	v_cvt_pk_bf16_f32 v82, v95, s0
	v_lshl_add_u64 v[80:81], v[148:149], 0, v[138:139]
	global_store_short v[80:81], v82, off
	ds_read_b128 v[80:83], v119 offset:4608
	ds_read_b128 v[88:91], v119 offset:4672
	s_waitcnt lgkmcnt(1)
	v_mfma_f32_16x16x32_bf16 v[80:83], v[80:83], v[72:75], 0
	s_waitcnt lgkmcnt(0)
	v_mfma_f32_16x16x32_bf16 v[80:83], v[88:91], v[68:71], v[80:83]
	v_lshl_add_u64 v[88:89], v[148:149], 0, v[140:141]
	s_nop 6
	v_fma_f32 v76, v76, v84, v80
	v_cvt_pk_bf16_f32 v76, v76, s0
	global_store_short v[88:89], v76, off
	v_fma_f32 v76, v77, v85, v81
	v_cvt_pk_bf16_f32 v80, v76, s0
	v_lshl_add_u64 v[76:77], v[148:149], 0, v[142:143]
	global_store_short v[76:77], v80, off
	v_fma_f32 v76, v78, v86, v82
	v_cvt_pk_bf16_f32 v78, v76, s0
	v_lshl_add_u64 v[76:77], v[148:149], 0, v[144:145]
	v_fmac_f32_e32 v83, v79, v87
	global_store_short v[76:77], v78, off
	v_cvt_pk_bf16_f32 v78, v83, s0
	v_lshl_add_u64 v[76:77], v[148:149], 0, v[146:147]
	global_store_short v[76:77], v78, off
	v_mov_b32_e32 v76, s17
	ds_read_b32 v76, v76
	v_add_u32_e32 v83, v161, v155
	v_add_u32_e32 v82, v181, v182
	v_add_u32_e32 v84, v161, v182
	v_add_u32_e32 v85, v161, v183
	v_add_u32_e32 v86, v161, v162
	ds_read_b128 v[88:91], v83 offset:34816
	ds_read_b128 v[92:95], v82 offset:34816
	ds_read_b128 v[96:99], v190 offset:34816
	ds_read_b128 v[100:103], v191 offset:34816
	ds_read_b128 v[104:107], v83 offset:44096
	ds_read_b128 v[194:197], v84 offset:46400
	ds_read_b128 v[198:201], v85 offset:48704
	ds_read_b128 v[232:235], v86 offset:51008
	s_waitcnt lgkmcnt(8)
	v_pk_mul_f32 v[30:31], v[30:31], v[76:77] op_sel_hi:[1,0]
	v_pk_mul_f32 v[28:29], v[28:29], v[76:77] op_sel_hi:[1,0]
	v_pk_mul_f32 v[42:43], v[42:43], v[76:77] op_sel_hi:[1,0]
	v_pk_mul_f32 v[40:41], v[40:41], v[76:77] op_sel_hi:[1,0]
	v_pk_mul_f32 v[34:35], v[34:35], v[76:77] op_sel_hi:[1,0]
	v_pk_mul_f32 v[32:33], v[32:33], v[76:77] op_sel_hi:[1,0]
	v_pk_mul_f32 v[38:39], v[38:39], v[76:77] op_sel_hi:[1,0]
	v_pk_mul_f32 v[36:37], v[36:37], v[76:77] op_sel_hi:[1,0]
	v_pk_mul_f32 v[58:59], v[58:59], v[76:77] op_sel_hi:[1,0]
	v_pk_mul_f32 v[56:57], v[56:57], v[76:77] op_sel_hi:[1,0]
	v_pk_mul_f32 v[54:55], v[54:55], v[76:77] op_sel_hi:[1,0]
	v_pk_mul_f32 v[52:53], v[52:53], v[76:77] op_sel_hi:[1,0]
	v_pk_mul_f32 v[46:47], v[46:47], v[76:77] op_sel_hi:[1,0]
	v_pk_mul_f32 v[44:45], v[44:45], v[76:77] op_sel_hi:[1,0]
	v_pk_mul_f32 v[50:51], v[50:51], v[76:77] op_sel_hi:[1,0]
	v_pk_mul_f32 v[48:49], v[48:49], v[76:77] op_sel_hi:[1,0]
	s_waitcnt lgkmcnt(7)
	v_mfma_f32_16x16x32_bf16 v[28:31], v[88:91], v[72:75], v[28:31]
	ds_read_b128 v[88:91], v83 offset:34880
	s_waitcnt lgkmcnt(7)
	v_mfma_f32_16x16x32_bf16 v[40:43], v[92:95], v[72:75], v[40:43]
	ds_read_b128 v[92:95], v82 offset:34880
	s_waitcnt lgkmcnt(7)
	v_mfma_f32_16x16x32_bf16 v[32:35], v[96:99], v[72:75], v[32:35]
	ds_read_b128 v[96:99], v190 offset:34880
	s_waitcnt lgkmcnt(7)
	v_mfma_f32_16x16x32_bf16 v[36:39], v[100:103], v[72:75], v[36:39]
	ds_read_b128 v[100:103], v191 offset:34880
	s_waitcnt lgkmcnt(7)
	v_mfma_f32_16x16x32_bf16 v[56:59], v[104:107], v[72:75], v[56:59]
	ds_read_b128 v[104:107], v83 offset:44032
	s_waitcnt lgkmcnt(7)
	v_mfma_f32_16x16x32_bf16 v[52:55], v[194:197], v[72:75], v[52:55]
	ds_read_b128 v[194:197], v84 offset:46336
	s_waitcnt lgkmcnt(7)
	v_mfma_f32_16x16x32_bf16 v[44:47], v[198:201], v[72:75], v[44:47]
	ds_read_b128 v[198:201], v85 offset:48640
	s_waitcnt lgkmcnt(7)
	v_mfma_f32_16x16x32_bf16 v[48:51], v[232:235], v[72:75], v[48:51]
	ds_read_b128 v[232:235], v86 offset:50944
	s_waitcnt lgkmcnt(7)
	v_mfma_f32_16x16x32_bf16 v[28:31], v[88:91], v[68:71], v[28:31]
	s_waitcnt lgkmcnt(6)
	v_mfma_f32_16x16x32_bf16 v[40:43], v[92:95], v[68:71], v[40:43]
	s_waitcnt lgkmcnt(5)
	v_mfma_f32_16x16x32_bf16 v[32:35], v[96:99], v[68:71], v[32:35]
	s_waitcnt lgkmcnt(4)
	v_mfma_f32_16x16x32_bf16 v[36:39], v[100:103], v[68:71], v[36:39]
	s_waitcnt lgkmcnt(3)
	v_mfma_f32_16x16x32_bf16 v[56:59], v[104:107], v[68:71], v[56:59]
	s_waitcnt lgkmcnt(2)
	v_mfma_f32_16x16x32_bf16 v[52:55], v[194:197], v[68:71], v[52:55]
	s_waitcnt lgkmcnt(1)
	v_mfma_f32_16x16x32_bf16 v[44:47], v[198:201], v[68:71], v[44:47]
	s_waitcnt lgkmcnt(0)
	v_mfma_f32_16x16x32_bf16 v[48:51], v[232:235], v[68:71], v[48:51]
	s_waitcnt vmcnt(19)
	v_mov_b64_e32 v[74:75], v[66:67]
	v_mov_b64_e32 v[70:71], v[62:63]
	v_mov_b64_e32 v[72:73], v[64:65]
	v_mov_b64_e32 v[68:69], v[60:61]
	s_cbranch_scc0 .LBB0_1135

; #define LAS __attribute__((address_space(3)))
; template <int L>
; __device__ NOINL void hyena_item(const LAS Params* lp, int l, int c, LAS unsigned char* lds) {
;     ...
;     __syncthreads();
;     for (int i = tid; i < 16 * L / 8; i += 512) { const int bb = i / (L / 8), s8 = (i % (L / 8)) * 8; *(LAS u32x4*)(lds + UOFF + bb * USB + s8 * 2) = *(const u32x4*)(hT + ((size_t)c * NB + bb) * L + s8); }
.LBB0_1231:
	v_ashrrev_i32_e32 v31, 31, v8
	v_add_u32_sdwa v33, v8, v31 dst_sel:DWORD dst_unused:UNUSED_PAD src0_sel:DWORD src1_sel:BYTE_3
	v_ashrrev_i32_e32 v30, 8, v33
	v_mul_i32_i24_e32 v33, 0x100, v30
	v_ashrrev_i32_e32 v31, 31, v30
	v_lshlrev_b32_e32 v32, 3, v33
	v_lshl_add_u64 v[34:35], v[30:31], 0, s[6:7]
	v_sub_u32_e32 v36, v0, v32
	v_lshlrev_b64 v[38:39], 12, v[34:35]
	v_lshl_add_u64 v[34:35], s[48:49], 0, v[38:39]
	v_ashrrev_i32_e32 v37, 31, v36
	v_lshl_add_u64 v[38:39], v[36:37], 1, v[34:35]
	global_load_dwordx4 v[34:37], v[38:39], off
	v_add_u32_e32 v39, 0x200, v8
	v_mov_b32_e32 v32, v39
	v_add_u32_e32 v38, 0x1000, v0
	v_ashrrev_i32_e32 v39, 31, v32
	v_add_u32_sdwa v41, v32, v39 dst_sel:DWORD dst_unused:UNUSED_PAD src0_sel:DWORD src1_sel:BYTE_3
	v_ashrrev_i32_e32 v42, 8, v41
	v_mul_i32_i24_e32 v39, 0x100, v42
	v_ashrrev_i32_e32 v43, 31, v42
	v_lshlrev_b32_e32 v40, 3, v39
	v_lshl_add_u64 v[44:45], v[42:43], 0, s[6:7]
	v_sub_u32_e32 v46, v38, v40
	v_lshlrev_b64 v[40:41], 12, v[44:45]
	v_lshl_add_u64 v[44:45], s[48:49], 0, v[40:41]
	v_ashrrev_i32_e32 v47, 31, v46
	v_lshl_add_u64 v[40:41], v[46:47], 1, v[44:45]
	global_load_dwordx4 v[44:47], v[40:41], off
	v_add_u32_e32 v41, 0x200, v32
	v_mov_b32_e32 v32, v41
	v_add_u32_e32 v40, 0x1000, v38
	v_ashrrev_i32_e32 v41, 31, v32
	v_add_u32_sdwa v49, v32, v41 dst_sel:DWORD dst_unused:UNUSED_PAD src0_sel:DWORD src1_sel:BYTE_3
	v_ashrrev_i32_e32 v50, 8, v49
	v_mul_i32_i24_e32 v41, 0x100, v50
	v_ashrrev_i32_e32 v51, 31, v50
	v_lshlrev_b32_e32 v38, 3, v41
	v_lshl_add_u64 v[48:49], v[50:51], 0, s[6:7]
	v_sub_u32_e32 v52, v40, v38
	v_lshlrev_b64 v[54:55], 12, v[48:49]
	v_lshl_add_u64 v[48:49], s[48:49], 0, v[54:55]
	v_ashrrev_i32_e32 v53, 31, v52
	v_lshl_add_u64 v[54:55], v[52:53], 1, v[48:49]
	global_load_dwordx4 v[56:59], v[54:55], off
	v_add_u32_e32 v49, 0x200, v32
	v_mov_b32_e32 v32, v49
	v_add_u32_e32 v38, 0x1000, v40
	v_ashrrev_i32_e32 v49, 31, v32
	v_add_u32_sdwa v53, v32, v49 dst_sel:DWORD dst_unused:UNUSED_PAD src0_sel:DWORD src1_sel:BYTE_3
	v_ashrrev_i32_e32 v48, 8, v53
	v_mul_i32_i24_e32 v53, 0x100, v48
	v_ashrrev_i32_e32 v49, 31, v48
	v_lshlrev_b32_e32 v40, 3, v53
	v_lshl_add_u64 v[54:55], v[48:49], 0, s[6:7]
	v_sub_u32_e32 v60, v38, v40
	v_lshlrev_b64 v[62:63], 12, v[54:55]
	v_lshl_add_u64 v[54:55], s[48:49], 0, v[62:63]
	v_ashrrev_i32_e32 v61, 31, v60
	v_lshl_add_u64 v[62:63], v[60:61], 1, v[54:55]
	global_load_dwordx4 v[64:67], v[62:63], off
	v_add_u32_e32 v55, 0x200, v32
	v_mov_b32_e32 v32, v55
	v_add_u32_e32 v40, 0x1000, v38
	v_ashrrev_i32_e32 v55, 31, v32
	v_add_u32_sdwa v61, v32, v55 dst_sel:DWORD dst_unused:UNUSED_PAD src0_sel:DWORD src1_sel:BYTE_3
	v_ashrrev_i32_e32 v54, 8, v61
	v_mul_i32_i24_e32 v61, 0x100, v54
	v_ashrrev_i32_e32 v55, 31, v54
	v_lshlrev_b32_e32 v38, 3, v61
	v_lshl_add_u64 v[62:63], v[54:55], 0, s[6:7]
	v_sub_u32_e32 v68, v40, v38
	v_lshlrev_b64 v[70:71], 12, v[62:63]
	v_lshl_add_u64 v[62:63], s[48:49], 0, v[70:71]
	v_ashrrev_i32_e32 v69, 31, v68
	v_lshl_add_u64 v[70:71], v[68:69], 1, v[62:63]
	global_load_dwordx4 v[72:75], v[70:71], off
	v_add_u32_e32 v63, 0x200, v32
	v_mov_b32_e32 v32, v63
	v_add_u32_e32 v38, 0x1000, v40
	v_ashrrev_i32_e32 v63, 31, v32
	v_add_u32_sdwa v69, v32, v63 dst_sel:DWORD dst_unused:UNUSED_PAD src0_sel:DWORD src1_sel:BYTE_3
	v_ashrrev_i32_e32 v62, 8, v69
	v_mul_i32_i24_e32 v69, 0x100, v62
	v_ashrrev_i32_e32 v63, 31, v62
	v_lshlrev_b32_e32 v40, 3, v69
	v_lshl_add_u64 v[70:71], v[62:63], 0, s[6:7]
	v_sub_u32_e32 v76, v38, v40
	v_lshlrev_b64 v[78:79], 12, v[70:71]
	v_lshl_add_u64 v[70:71], s[48:49], 0, v[78:79]
	v_ashrrev_i32_e32 v77, 31, v76
	v_lshl_add_u64 v[78:79], v[76:77], 1, v[70:71]
	global_load_dwordx4 v[80:83], v[78:79], off
	v_add_u32_e32 v71, 0x200, v32
	v_mov_b32_e32 v32, v71
	v_add_u32_e32 v40, 0x1000, v38
	v_ashrrev_i32_e32 v71, 31, v32
	v_add_u32_sdwa v77, v32, v71 dst_sel:DWORD dst_unused:UNUSED_PAD src0_sel:DWORD src1_sel:BYTE_3
	v_ashrrev_i32_e32 v70, 8, v77
	v_mul_i32_i24_e32 v77, 0x100, v70
	v_ashrrev_i32_e32 v71, 31, v70
	v_lshlrev_b32_e32 v38, 3, v77
	v_lshl_add_u64 v[78:79], v[70:71], 0, s[6:7]
	v_sub_u32_e32 v84, v40, v38
	v_lshlrev_b64 v[86:87], 12, v[78:79]
	v_lshl_add_u64 v[78:79], s[48:49], 0, v[86:87]
	v_ashrrev_i32_e32 v85, 31, v84
	v_lshl_add_u64 v[86:87], v[84:85], 1, v[78:79]
	global_load_dwordx4 v[88:91], v[86:87], off
	v_add_u32_e32 v79, 0x200, v32
	v_mov_b32_e32 v32, v79
	v_add_u32_e32 v38, 0x1000, v40
	v_ashrrev_i32_e32 v79, 31, v32
	v_add_u32_sdwa v85, v32, v79 dst_sel:DWORD dst_unused:UNUSED_PAD src0_sel:DWORD src1_sel:BYTE_3
	v_ashrrev_i32_e32 v78, 8, v85
	v_mul_i32_i24_e32 v85, 0x100, v78
	v_ashrrev_i32_e32 v79, 31, v78
	v_lshlrev_b32_e32 v40, 3, v85
	v_lshl_add_u64 v[86:87], v[78:79], 0, s[6:7]
	v_sub_u32_e32 v92, v38, v40
	v_lshlrev_b64 v[94:95], 12, v[86:87]
	v_lshl_add_u64 v[86:87], s[48:49], 0, v[94:95]
	v_ashrrev_i32_e32 v93, 31, v92
	v_lshl_add_u64 v[94:95], v[92:93], 1, v[86:87]
	global_load_dwordx4 v[96:99], v[94:95], off
	v_mul_i32_i24_e32 v14, 0x1010, v30
	v_lshlrev_b32_e32 v9, 4, v33
	v_sub_u32_e32 v9, v14, v9
	v_add_u32_e32 v9, v3, v9
	v_add_u32_e32 v3, 0x2000, v3
	s_waitcnt vmcnt(7)
	ds_write_b128 v9, v[34:37]
	v_mul_i32_i24_e32 v14, 0x1010, v42
	v_lshlrev_b32_e32 v9, 4, v39
	v_sub_u32_e32 v9, v14, v9
	v_add_u32_e32 v9, v3, v9
	v_add_u32_e32 v3, 0x2000, v3
	s_waitcnt vmcnt(6)
	ds_write_b128 v9, v[44:47]
	v_mul_i32_i24_e32 v14, 0x1010, v50
	v_lshlrev_b32_e32 v9, 4, v41
	v_sub_u32_e32 v9, v14, v9
	v_add_u32_e32 v9, v3, v9
	v_add_u32_e32 v3, 0x2000, v3
	s_waitcnt vmcnt(5)
	ds_write_b128 v9, v[56:59]
	v_mul_i32_i24_e32 v14, 0x1010, v48
	v_lshlrev_b32_e32 v9, 4, v53
	v_sub_u32_e32 v9, v14, v9
	v_add_u32_e32 v9, v3, v9
	v_add_u32_e32 v3, 0x2000, v3
	s_waitcnt vmcnt(4)
	ds_write_b128 v9, v[64:67]
	v_mul_i32_i24_e32 v14, 0x1010, v54
	v_lshlrev_b32_e32 v9, 4, v61
	v_sub_u32_e32 v9, v14, v9
	v_add_u32_e32 v9, v3, v9
	v_add_u32_e32 v3, 0x2000, v3
	s_waitcnt vmcnt(3)
	ds_write_b128 v9, v[72:75]
	v_mul_i32_i24_e32 v14, 0x1010, v62
	v_lshlrev_b32_e32 v9, 4, v69
	v_sub_u32_e32 v9, v14, v9
	v_add_u32_e32 v9, v3, v9
	v_add_u32_e32 v3, 0x2000, v3
	s_waitcnt vmcnt(2)
	ds_write_b128 v9, v[80:83]
	v_mul_i32_i24_e32 v14, 0x1010, v70
	v_lshlrev_b32_e32 v9, 4, v77
	v_sub_u32_e32 v9, v14, v9
	v_add_u32_e32 v9, v3, v9
	v_add_u32_e32 v3, 0x2000, v3
	s_waitcnt vmcnt(1)
	ds_write_b128 v9, v[88:91]
	v_mul_i32_i24_e32 v14, 0x1010, v78
	v_lshlrev_b32_e32 v9, 4, v85
	v_add_u32_e32 v15, 0x200, v32
	v_sub_u32_e32 v9, v14, v9
	v_mov_b32_e32 v8, v15
	v_add_u32_e32 v0, 0x1000, v38
	v_add_u32_e32 v9, v3, v9
	v_add_u32_e32 v3, 0x2000, v3
	s_waitcnt vmcnt(0)
	ds_write_b128 v9, v[96:99]

; #define LAS __attribute__((address_space(3)))
; template <int L>
; __device__ NOINL void hyena_item(const LAS Params* lp, int l, int c, LAS unsigned char* lds) {
;     ...
;         const bf16_t* Fr = Fg + ((size_t)order * 256 + c) * (2 * L);
;         for (int i = tid; i < 2 * L + 8; i += 512) {
;             const bf16_t v = i < 2 * L ? Fr[i] : (bf16_t)0;
; #pragma unroll
;             for (int r = 0; r < 8; ++r) if (i - r >= 0) *(LAS bf16_t*)(lds + r * FSB + (i - r) * 2) = v;
;         }
.LBB0_1234:
	s_and_saveexec_b64 s[52:53], s[44:45]
	s_cbranch_execz .LBB0_1255
	s_lshl_b32 s3, s1, 20
	s_add_i32 s6, s3, s0
	v_lshl_add_u64 v[8:9], s[6:7], 1, v[120:121]
	global_load_ushort v186, v[8:9], off
	global_load_ushort v187, v[8:9], off offset:1024
	global_load_ushort v188, v[8:9], off offset:2048
	global_load_ushort v189, v[8:9], off offset:3072
	v_add_co_u32_e32 v176, vcc, 0x1000, v8
	s_nop 1
	v_addc_co_u32_e32 v177, vcc, 0, v9, vcc
	global_load_ushort v190, v[176:177], off
	global_load_ushort v191, v[176:177], off offset:1024
	global_load_ushort v192, v[176:177], off offset:2048
	global_load_ushort v193, v[176:177], off offset:3072
	v_add_u32_e32 v178, 0x2000, v127
	s_waitcnt vmcnt(7)
	ds_write_b16 v127, v186
	v_cmp_lt_i32_e32 vcc, 0, v2
	s_and_saveexec_b64 s[54:55], vcc
	ds_write_b16 v127, v186 offset:8222
	s_or_b64 exec, exec, s[54:55]
	v_cmp_lt_i32_e32 vcc, 1, v2
	s_and_saveexec_b64 s[54:55], vcc
	ds_write_b16 v127, v186 offset:16444
	s_or_b64 exec, exec, s[54:55]
	v_cmp_lt_i32_e32 vcc, 2, v2
	s_and_saveexec_b64 s[54:55], vcc
	ds_write_b16 v127, v186 offset:24666
	s_or_b64 exec, exec, s[54:55]
	v_cmp_lt_i32_e32 vcc, 3, v2
	s_and_saveexec_b64 s[54:55], vcc
	ds_write_b16 v127, v186 offset:32888
	s_or_b64 exec, exec, s[54:55]
	v_cmp_lt_i32_e32 vcc, 4, v2
	s_and_saveexec_b64 s[54:55], vcc
	ds_write_b16 v127, v186 offset:41110
	s_or_b64 exec, exec, s[54:55]
	v_cmp_lt_i32_e32 vcc, 5, v2
	s_and_saveexec_b64 s[54:55], vcc
	ds_write_b16 v127, v186 offset:49332
	s_or_b64 exec, exec, s[54:55]
	v_cmp_lt_i32_e32 vcc, 6, v2
	s_and_saveexec_b64 s[54:55], vcc
	ds_write_b16 v127, v186 offset:57554
	s_or_b64 exec, exec, s[54:55]
	s_waitcnt vmcnt(6)
	ds_write_b16 v127, v187 offset:1024
	ds_write_b16 v127, v187 offset:9246
	ds_write_b16 v127, v187 offset:17468
	ds_write_b16 v127, v187 offset:25690
	ds_write_b16 v127, v187 offset:33912
	ds_write_b16 v127, v187 offset:42134
	ds_write_b16 v127, v187 offset:50356
	ds_write_b16 v127, v187 offset:58578
	s_waitcnt vmcnt(5)
	ds_write_b16 v127, v188 offset:2048
	ds_write_b16 v127, v188 offset:10270
	ds_write_b16 v127, v188 offset:18492
	ds_write_b16 v127, v188 offset:26714
	ds_write_b16 v127, v188 offset:34936
	ds_write_b16 v127, v188 offset:43158
	ds_write_b16 v127, v188 offset:51380
	ds_write_b16 v127, v188 offset:59602
	s_waitcnt vmcnt(4)
	ds_write_b16 v127, v189 offset:3072
	ds_write_b16 v127, v189 offset:11294
	ds_write_b16 v127, v189 offset:19516
	ds_write_b16 v127, v189 offset:27738
	ds_write_b16 v127, v189 offset:35960
	ds_write_b16 v127, v189 offset:44182
	ds_write_b16 v127, v189 offset:52404
	ds_write_b16 v127, v189 offset:60626
	s_waitcnt vmcnt(3)
	ds_write_b16 v127, v190 offset:4096
	ds_write_b16 v127, v190 offset:12318
	ds_write_b16 v127, v190 offset:20540
	ds_write_b16 v127, v190 offset:28762
	ds_write_b16 v127, v190 offset:36984
	ds_write_b16 v127, v190 offset:45206
	ds_write_b16 v127, v190 offset:53428
	ds_write_b16 v127, v190 offset:61650
	s_waitcnt vmcnt(2)
	ds_write_b16 v127, v191 offset:5120
	ds_write_b16 v127, v191 offset:13342
	ds_write_b16 v127, v191 offset:21564
	ds_write_b16 v127, v191 offset:29786
	ds_write_b16 v127, v191 offset:38008
	ds_write_b16 v127, v191 offset:46230
	ds_write_b16 v127, v191 offset:54452
	ds_write_b16 v127, v191 offset:62674
	s_waitcnt vmcnt(1)
	ds_write_b16 v127, v192 offset:6144
	ds_write_b16 v127, v192 offset:14366
	ds_write_b16 v127, v192 offset:22588
	ds_write_b16 v127, v192 offset:30810
	ds_write_b16 v127, v192 offset:39032
	ds_write_b16 v127, v192 offset:47254
	ds_write_b16 v127, v192 offset:55476
	ds_write_b16 v127, v192 offset:63698
	s_waitcnt vmcnt(0)
	ds_write_b16 v127, v193 offset:7168
	ds_write_b16 v127, v193 offset:15390
	ds_write_b16 v127, v193 offset:23612
	ds_write_b16 v127, v193 offset:31834
	ds_write_b16 v127, v193 offset:40056
	ds_write_b16 v127, v193 offset:48278
	ds_write_b16 v127, v193 offset:56500
	ds_write_b16 v127, v193 offset:64722
	v_cmp_gt_i32_e32 vcc, 8, v2
	s_and_saveexec_b64 s[54:55], vcc
	ds_write_b16 v178, v1
	ds_write_b16 v178, v1 offset:8222
	ds_write_b16 v178, v1 offset:16444
	ds_write_b16 v178, v1 offset:24666
	ds_write_b16 v178, v1 offset:32888
	ds_write_b16 v178, v1 offset:41110
	ds_write_b16 v178, v1 offset:49332
	ds_write_b16 v178, v1 offset:57554
	s_or_b64 exec, exec, s[54:55]
